# adds one static s_setprio 1 for waves 4-7 during the HGRN scan phase (reset at phase end)
# baseline (speedup 1.0000x reference)
; #define LAS __attribute__((address_space(3)))
; __device__ __forceinline__ int lane_id_() { int l; asm volatile("v_mbcnt_lo_u32_b32 %0, -1, 0\n\tv_mbcnt_hi_u32_b32 %0, -1, %0" : "=v"(l)); return l; }
; __device__ __forceinline__ void hgrn_chunked_bh(const Ctx& F, int b, int h) {
;     const bf16_t* proj = (const bf16_t*)(F.ws + WS_BIG); const float* lb = (const float*)(F.ws + WS_LB);
;     bf16_t* Y = (bf16_t*)(F.ws + WS_HB);
;     LAS unsigned char* L = F.lds;
;     const int lane = lane_id_(), w = F.wid, tid = w * 64 + lane, c16 = lane & 15, g = lane >> 4;
;     const int pt = lane & 31, phalf = lane >> 5, k0 = 16 * w + 8 * phalf;
;     float lb8[8];
;     { const f32x4 l0 = *(const f32x4*)(lb + h * 128 + k0), l1 = *(const f32x4*)(lb + h * 128 + k0 + 4); lb8[0] = l0[0]; lb8[1] = l0[1]; lb8[2] = l0[2]; lb8[3] = l0[3]; lb8[4] = l1[0]; lb8[5] = l1[1]; lb8[6] = l1[2]; lb8[7] = l1[3]; }
;     const float gn0 = F_hg_norm[lane], gn1 = F_hg_norm[64 + lane];
;     f32x4 st[8];
; #pragma unroll
;     for (int i = 0; i < 8; ++i) st[i] = (f32x4){0.f, 0.f, 0.f, 0.f};
;     u32x4 rq, rf, rv;
;     { const bf16_t* p = proj + ((size_t)b * S + pt) * IN_ODD + h * 128 + k0; rq = *(const u32x4*)p; rf = *(const u32x4*)(p + 1024); rv = *(const u32x4*)(p + 2048); }
;     bf16_t gqp[4][2] = {};
;     for (int c = 0; c < S / 32; ++c) {
.LBB0_1373:
	s_cmp_lt_i32 s84, 13
	s_cselect_b64 s[0:1], -1, 0
	s_cmp_gt_i32 s85, 12
	s_cselect_b64 s[4:5], -1, 0
	s_and_b64 s[0:1], s[0:1], s[4:5]
	s_andn2_b64 vcc, exec, s[0:1]
	s_cbranch_vccnz .LBB0_1459
	s_mov_b64 s[56:57], s[88:89]
	s_cmpk_gt_i32 s2, 0xff
	s_cbranch_scc1 .LBB0_1403
	s_cmp_lt_u32 s50, 4
	s_cbranch_scc1 .Lhg_prio_done
	s_setprio 1
.Lhg_prio_done:
	s_add_u32 s0, s46, 0x200000
	s_mov_b32 s51, 0
	s_addc_u32 s1, s47, 0
	s_lshl_b32 s3, s50, 4
	s_and_b32 s33, s86, 0xffffffc0
	s_add_i32 s48, s50, 8
	s_add_i32 s49, s50, 16
	s_add_i32 s54, s50, 24
	s_lshl_b64 s[4:5], s[50:51], 13
	s_add_u32 s55, s46, s4
	s_addc_u32 s68, s47, s5
	s_lshl_b32 s69, s2, 7
	s_lshl_b32 s70, s90, 7
	s_lshl_b32 s4, s50, 5
	s_add_u32 s58, s46, s4
	s_mul_i32 s43, s50, 0x210
	s_addc_u32 s59, s47, 0
	s_movk_i32 s71, 0x1000
	s_movk_i32 s72, 0x50
	s_mov_b32 s73, 0x800000
	s_mov_b32 s74, 0x3f317217
	s_mov_b32 s75, 0x7f800000
	s_mov_b32 s76, 0xc2700000
	v_mov_b32_e32 v110, 0x358637bd
	s_mov_b32 s77, 0xf800000
	v_mov_b32_e32 v111, 0x260
	s_mov_b32 s78, 0x5040100
	v_mov_b32_e32 v112, 0x41b17218
	v_mov_b32_e32 v113, 0x42700000
	s_mov_b32 s79, s2
	s_branch .LBB0_1377

; #define LAS __attribute__((address_space(3)))
; __device__ __forceinline__ int lane_id_() { int l; asm volatile("v_mbcnt_lo_u32_b32 %0, -1, 0\n\tv_mbcnt_hi_u32_b32 %0, -1, %0" : "=v"(l)); return l; }
; __device__ __forceinline__ unsigned xb_add(unsigned* p, unsigned v) { return __hip_atomic_fetch_add(p, v, __ATOMIC_RELAXED, __HIP_MEMORY_SCOPE_AGENT); }
; __device__ __forceinline__ unsigned xb_xcc_id() { return (unsigned)__builtin_amdgcn_s_getreg((3 << 11) | 20) & 0xFu; }
; __device__ __forceinline__ void grid_bar(const Ctx& F, unsigned) {
;     asm volatile("s_waitcnt vmcnt(0) lgkmcnt(0)" ::: "memory");
;     __syncthreads();
;     if (F.wid == 0) {
;         if (lane_id_() == 0) {
;             unsigned* bar = (unsigned*)(F.ws + WS_BAR);
;             volatile LAS unsigned* st = (volatile LAS unsigned*)(F.lds + LDS_BYTES - 64);
;             const unsigned x = xb_xcc_id();
;             __builtin_amdgcn_s_waitcnt(0);
;             unsigned nloc = st[0], nx = st[1];
;             if (nloc == 0u) { xcd_barrier_complete(bar, x, nloc, nx); st[0] = nloc; st[1] = nx; }
;             const unsigned old = xb_add(&bar[XB_XSUB(x)], 1u);
.LBB0_1403:
	s_setprio 0
	v_readlane_b32 s70, v254, 4
	s_cmp_eq_u32 s85, 13
	v_readlane_b32 s71, v254, 5
	s_cbranch_scc1 .LBB0_1459
	s_waitcnt vmcnt(0) lgkmcnt(0)
	s_cmp_lt_u32 s86, 64
	s_waitcnt vmcnt(0) lgkmcnt(0)
	s_barrier
	s_cbranch_scc0 .LBB0_1458
	v_mbcnt_lo_u32_b32 v0, -1, 0
	v_mbcnt_hi_u32_b32 v0, -1, v0
	s_nop 0
	v_cmp_eq_u32_e32 vcc, 0, v0
	s_and_saveexec_b64 s[4:5], vcc
	s_cbranch_execz .LBB0_1457
	s_add_u32 s6, s46, 0x300200
	s_addc_u32 s7, s47, 0
	s_add_i32 s1, 0, 0x23fc0
	v_mov_b32_e32 v0, s1
	s_getreg_b32 s0, hwreg(HW_REG_XCC_ID, 0, 4)
	s_waitcnt vmcnt(0) expcnt(0) lgkmcnt(0)
	ds_read_b32 v2, v0
	s_add_i32 s1, 0, 0x23fc4
	v_mov_b32_e32 v0, s1
	ds_read_b32 v0, v0
	s_and_b32 s0, s0, 15
	s_waitcnt lgkmcnt(1)
	v_cmp_ne_u32_e32 vcc, 0, v2
	s_cbranch_vccnz .LBB0_1421
	s_add_u32 s8, s46, 0x300400
	s_addc_u32 s9, s47, 0
	s_add_u32 s10, s46, 0x300500
	s_addc_u32 s11, s47, 0
	s_add_u32 s12, s46, 0x300600
	s_addc_u32 s13, s47, 0
	s_add_u32 s14, s46, 0x300700
	s_addc_u32 s15, s47, 0
	s_add_u32 s16, s46, 0x300800
	s_addc_u32 s17, s47, 0
	s_add_u32 s18, s46, 0x300900
	s_addc_u32 s19, s47, 0
	s_add_u32 s20, s46, 0x300a00
	s_addc_u32 s21, s47, 0
	s_add_u32 s22, s46, 0x300b00
	s_addc_u32 s23, s47, 0
	s_add_u32 s24, s46, 0x300c00
	s_addc_u32 s25, s47, 0
	s_add_u32 s26, s46, 0x300d00
	s_addc_u32 s27, s47, 0
	s_add_u32 s28, s46, 0x300e00
	s_addc_u32 s29, s47, 0
	s_add_u32 s30, s46, 0x300f00
	s_addc_u32 s31, s47, 0
	s_add_u32 s34, s46, 0x301000
	s_addc_u32 s35, s47, 0
	s_add_u32 s36, s46, 0x301100
	s_addc_u32 s37, s47, 0
	s_add_u32 s38, s46, 0x301200
	s_addc_u32 s39, s47, 0
	s_add_u32 s40, s46, 0x301300
	s_addc_u32 s41, s47, 0
	s_mov_b32 s1, 1
	v_mov_b32_e32 v16, 0
	s_branch .LBB0_1409
